# ssm_p3: the park/finalize pair at the block midpoint (iteration 3 -> 4) goes through LDS instead of global scratch, no store-ack wait between the two loops
# speedup vs baseline: 1.0058x; 1.0014x over previous
; __device__ __forceinline__ unsigned pk2(float lo, float hi) { const f32x2 v = {lo, hi}; return __builtin_bit_cast(unsigned, __builtin_convertvector(v, bf16x2_t)); }
; __device__ __forceinline__ float bflo(unsigned w) { return __uint_as_float(w << 16); }
; __device__ __forceinline__ float bfhi(unsigned w) { return __uint_as_float(w & 0xffff0000u); }
; #define LDS_FENCE() asm volatile("s_waitcnt lgkmcnt(0)" ::: "memory")
; template <bool BWD, int MODE  >
; __device__ __forceinline__ void ssm_pass(const bf16* proj, int rowbase, int g, const bf16x8* BBp, const bf16x8* CCp, float ar, float ai, float& sr, float& si,
;                                          LAS unsigned* XS, int lane, f32x4* ysc, const float* Dp, bf16* zbuf) {
;     ...
;     for (int c = 0; c < 16; ++c) {
;         const int ch = BWD ? 15 - c : c;
;         bf16x8 unext = ucur;
;         if (c < 15) unext = *(const bf16x8*)(up + (size_t)(BWD ? ch - 1 : ch + 1) * 32 * DIN);
;         f32x4 y0 = (f32x4){0.f, 0.f, 0.f, 0.f}, y1 = y0; bf16 uvl[8];
;         if (MODE == 2) {
;             y0 = ysc[(ch * 2 + 0) * 64 + lane]; y1 = ysc[(ch * 2 + 1) * 64 + lane];
; #pragma unroll
;             for (int q = 0; q < 8; ++q) uvl[q] = proj[(size_t)(rowbase + 32 * ch + 16 * (q >> 2) + 4 * (lane >> 4) + (q & 3)) * DIN + 768 + g * 16 + (lane & 15)];
;         }
;         f32x16 z16;
; #pragma unroll
;         for (int r = 0; r < 16; ++r) z16[r] = 0.f;
;         const f32x16 x0 = __builtin_amdgcn_mfma_f32_32x32x16_bf16(ucur, bb[0], z16, 0, 0, 0);
;         const f32x16 x1 = __builtin_amdgcn_mfma_f32_32x32x16_bf16(ucur, bb[1], z16, 0, 0, 0);
;         const f32x16 x2 = __builtin_amdgcn_mfma_f32_32x32x16_bf16(ucur, bb[2], z16, 0, 0, 0);
;         const f32x16 x3 = __builtin_amdgcn_mfma_f32_32x32x16_bf16(ucur, bb[3], z16, 0, 0, 0);
; #pragma unroll
;         for (int r = 0; r < 16; ++r) { const int t = crow(r, hi); XS[t * XS_STRIDE + ql] = pk2(x0[r], x2[r]); XS[t * XS_STRIDE + 32 + ql] = pk2(x1[r], x3[r]); }
;         LDS_FENCE();
; #pragma unroll
;         for (int tt = 0; tt < 32; ++tt) {
;             const int t = BWD ? 31 - tt : tt;
;             const unsigned v = XS[t * XS_STRIDE + lane];
;             const float nr = fmaf(ar, sr, fmaf(-ai, si, bflo(v))), ni = fmaf(ar, si, fmaf(ai, sr, bfhi(v)));
;             sr = nr; si = ni;
;             if (MODE > 0) XS[t * XS_STRIDE + lane] = pk2(sr, si);
.Lp3n_loopa:
	v_add_u32_e32 v156, v157, v156
	s_mov_b64 exec, s[60:61]
	global_load_dwordx4 v[138:141], v156, s[6:7]
	s_mov_b64 exec, s[62:63]
	global_load_dwordx4 v[142:145], v156, s[6:7]
	s_mov_b64 exec, -1
	v_mfma_f32_32x32x16_bf16 v[2:17], v[130:133], v[66:69], 0
	v_mfma_f32_32x32x16_bf16 v[18:33], v[130:133], v[70:73], 0
	v_mfma_f32_32x32x16_bf16 v[34:49], v[130:133], v[74:77], 0
	v_mfma_f32_32x32x16_bf16 v[50:65], v[130:133], v[78:81], 0
	v_mfma_f32_32x32x16_bf16 v[2:17], v[134:137], v[82:85], v[2:17]
	v_mfma_f32_32x32x16_bf16 v[18:33], v[134:137], v[86:89], v[18:33]
	v_mfma_f32_32x32x16_bf16 v[34:49], v[134:137], v[90:93], v[34:49]
	v_mfma_f32_32x32x16_bf16 v[50:65], v[134:137], v[94:97], v[50:65]
	s_nop 15
	s_nop 7
	v_fmac_f32_e32 v2, v150, v153
	v_fmac_f32_e32 v18, v151, v155
	v_fmac_f32_e32 v34, v147, v152
	v_fmac_f32_e32 v50, v149, v154
	v_fmac_f32_e32 v2, v146, v152
	v_fmac_f32_e32 v18, v148, v154
	v_fmac_f32_e32 v34, v146, v153
	v_fmac_f32_e32 v50, v148, v155
	v_fmac_f32_e32 v3, v150, v34
	v_fmac_f32_e32 v19, v151, v50
	v_fmac_f32_e32 v35, v147, v2
	v_fmac_f32_e32 v51, v149, v18
	v_fmac_f32_e32 v3, v146, v2
	v_fmac_f32_e32 v19, v148, v18
	v_fmac_f32_e32 v35, v146, v34
	v_fmac_f32_e32 v51, v148, v50
	v_cvt_pk_bf16_f32 v214, v2, v34
	v_cvt_pk_bf16_f32 v215, v18, v50
	ds_write2_b32 v158, v214, v215 offset0:0 offset1:32
	v_fmac_f32_e32 v4, v150, v35
	v_fmac_f32_e32 v20, v151, v51
	v_fmac_f32_e32 v36, v147, v3
	v_fmac_f32_e32 v52, v149, v19
	v_fmac_f32_e32 v4, v146, v3
	v_fmac_f32_e32 v20, v148, v19
	v_fmac_f32_e32 v36, v146, v35
	v_fmac_f32_e32 v52, v148, v51
	v_cvt_pk_bf16_f32 v216, v3, v35
	v_cvt_pk_bf16_f32 v217, v19, v51
	ds_write2_b32 v158, v216, v217 offset0:68 offset1:100
	v_fmac_f32_e32 v5, v150, v36
	v_fmac_f32_e32 v21, v151, v52
	v_fmac_f32_e32 v37, v147, v4
	v_fmac_f32_e32 v53, v149, v20
	v_fmac_f32_e32 v5, v146, v4
	v_fmac_f32_e32 v21, v148, v20
	v_fmac_f32_e32 v37, v146, v36
	v_fmac_f32_e32 v53, v148, v52
	v_cvt_pk_bf16_f32 v214, v4, v36
	v_cvt_pk_bf16_f32 v215, v20, v52
	ds_write2_b32 v158, v214, v215 offset0:136 offset1:168
	v_fmac_f32_e32 v6, v150, v37
	v_fmac_f32_e32 v22, v151, v53
	v_fmac_f32_e32 v38, v147, v5
	v_fmac_f32_e32 v54, v149, v21
	v_fmac_f32_e32 v6, v146, v5
	v_fmac_f32_e32 v22, v148, v21
	v_fmac_f32_e32 v38, v146, v37
	v_fmac_f32_e32 v54, v148, v53
	v_cvt_pk_bf16_f32 v216, v5, v37
	v_cvt_pk_bf16_f32 v217, v21, v53
	ds_write2_b32 v158, v216, v217 offset0:204 offset1:236
	v_fmac_f32_e32 v7, v150, v38
	v_fmac_f32_e32 v23, v151, v54
	v_fmac_f32_e32 v39, v147, v6
	v_fmac_f32_e32 v55, v149, v22
	v_fmac_f32_e32 v7, v146, v6
	v_fmac_f32_e32 v23, v148, v22
	v_fmac_f32_e32 v39, v146, v38
	v_fmac_f32_e32 v55, v148, v54
	v_cvt_pk_bf16_f32 v214, v6, v38
	v_cvt_pk_bf16_f32 v215, v22, v54
	ds_write2_b32 v159, v214, v215 offset0:0 offset1:32
	v_fmac_f32_e32 v8, v150, v39
	v_fmac_f32_e32 v24, v151, v55
	v_fmac_f32_e32 v40, v147, v7
	v_fmac_f32_e32 v56, v149, v23
	v_fmac_f32_e32 v8, v146, v7
	v_fmac_f32_e32 v24, v148, v23
	v_fmac_f32_e32 v40, v146, v39
	v_fmac_f32_e32 v56, v148, v55
	v_cvt_pk_bf16_f32 v216, v7, v39
	v_cvt_pk_bf16_f32 v217, v23, v55
	ds_write2_b32 v159, v216, v217 offset0:68 offset1:100
	v_fmac_f32_e32 v9, v150, v40
	v_fmac_f32_e32 v25, v151, v56
	v_fmac_f32_e32 v41, v147, v8
	v_fmac_f32_e32 v57, v149, v24
	v_fmac_f32_e32 v9, v146, v8
	v_fmac_f32_e32 v25, v148, v24
	v_fmac_f32_e32 v41, v146, v40
	v_fmac_f32_e32 v57, v148, v56
	v_cvt_pk_bf16_f32 v214, v8, v40
	v_cvt_pk_bf16_f32 v215, v24, v56
	ds_write2_b32 v159, v214, v215 offset0:136 offset1:168
	v_fmac_f32_e32 v10, v150, v41
	v_fmac_f32_e32 v26, v151, v57
	v_fmac_f32_e32 v42, v147, v9
	v_fmac_f32_e32 v58, v149, v25
	v_fmac_f32_e32 v10, v146, v9
	v_fmac_f32_e32 v26, v148, v25
	v_fmac_f32_e32 v42, v146, v41
	v_fmac_f32_e32 v58, v148, v57
	v_cvt_pk_bf16_f32 v216, v9, v41
	v_cvt_pk_bf16_f32 v217, v25, v57
	ds_write2_b32 v159, v216, v217 offset0:204 offset1:236
	v_fmac_f32_e32 v11, v150, v42
	v_fmac_f32_e32 v27, v151, v58
	v_fmac_f32_e32 v43, v147, v10
	v_fmac_f32_e32 v59, v149, v26
	v_fmac_f32_e32 v11, v146, v10
	v_fmac_f32_e32 v27, v148, v26
	v_fmac_f32_e32 v43, v146, v42
	v_fmac_f32_e32 v59, v148, v58
	v_cvt_pk_bf16_f32 v214, v10, v42
	v_cvt_pk_bf16_f32 v215, v26, v58
	ds_write2_b32 v160, v214, v215 offset0:0 offset1:32
	v_fmac_f32_e32 v12, v150, v43
	v_fmac_f32_e32 v28, v151, v59
	v_fmac_f32_e32 v44, v147, v11
	v_fmac_f32_e32 v60, v149, v27
	v_fmac_f32_e32 v12, v146, v11
	v_fmac_f32_e32 v28, v148, v27
	v_fmac_f32_e32 v44, v146, v43
	v_fmac_f32_e32 v60, v148, v59
	v_cvt_pk_bf16_f32 v216, v11, v43
	v_cvt_pk_bf16_f32 v217, v27, v59
	ds_write2_b32 v160, v216, v217 offset0:68 offset1:100
	v_fmac_f32_e32 v13, v150, v44
	v_fmac_f32_e32 v29, v151, v60
	v_fmac_f32_e32 v45, v147, v12
	v_fmac_f32_e32 v61, v149, v28
	v_fmac_f32_e32 v13, v146, v12
	v_fmac_f32_e32 v29, v148, v28
	v_fmac_f32_e32 v45, v146, v44
	v_fmac_f32_e32 v61, v148, v60
	v_cvt_pk_bf16_f32 v214, v12, v44
	v_cvt_pk_bf16_f32 v215, v28, v60
	ds_write2_b32 v160, v214, v215 offset0:136 offset1:168
	v_fmac_f32_e32 v14, v150, v45
	v_fmac_f32_e32 v30, v151, v61
	v_fmac_f32_e32 v46, v147, v13
	v_fmac_f32_e32 v62, v149, v29
	v_fmac_f32_e32 v14, v146, v13
	v_fmac_f32_e32 v30, v148, v29
	v_fmac_f32_e32 v46, v146, v45
	v_fmac_f32_e32 v62, v148, v61
	v_cvt_pk_bf16_f32 v216, v13, v45
	v_cvt_pk_bf16_f32 v217, v29, v61
	ds_write2_b32 v160, v216, v217 offset0:204 offset1:236
	v_fmac_f32_e32 v15, v150, v46
	v_fmac_f32_e32 v31, v151, v62
	v_fmac_f32_e32 v47, v147, v14
	v_fmac_f32_e32 v63, v149, v30
	v_fmac_f32_e32 v15, v146, v14
	v_fmac_f32_e32 v31, v148, v30
	v_fmac_f32_e32 v47, v146, v46
	v_fmac_f32_e32 v63, v148, v62
	v_cvt_pk_bf16_f32 v214, v14, v46
	v_cvt_pk_bf16_f32 v215, v30, v62
	ds_write2_b32 v161, v214, v215 offset0:0 offset1:32
	v_fmac_f32_e32 v16, v150, v47
	v_fmac_f32_e32 v32, v151, v63
	v_fmac_f32_e32 v48, v147, v15
	v_fmac_f32_e32 v64, v149, v31
	v_fmac_f32_e32 v16, v146, v15
	v_fmac_f32_e32 v32, v148, v31
	v_fmac_f32_e32 v48, v146, v47
	v_fmac_f32_e32 v64, v148, v63
	v_cvt_pk_bf16_f32 v216, v15, v47
	v_cvt_pk_bf16_f32 v217, v31, v63
	ds_write2_b32 v161, v216, v217 offset0:68 offset1:100
	v_fmac_f32_e32 v17, v150, v48
	v_fmac_f32_e32 v33, v151, v64
	v_fmac_f32_e32 v49, v147, v16
	v_fmac_f32_e32 v65, v149, v32
	v_fmac_f32_e32 v17, v146, v16
	v_fmac_f32_e32 v33, v148, v32
	v_fmac_f32_e32 v49, v146, v48
	v_fmac_f32_e32 v65, v148, v64
	v_cvt_pk_bf16_f32 v214, v16, v48
	v_cvt_pk_bf16_f32 v215, v32, v64
	ds_write2_b32 v161, v214, v215 offset0:136 offset1:168
	v_cvt_pk_bf16_f32 v216, v17, v49
	v_cvt_pk_bf16_f32 v217, v33, v65
	ds_write2_b32 v161, v216, v217 offset0:204 offset1:236
	v_mov_b32_e32 v152, v17
	v_mov_b32_e32 v153, v49
	v_mov_b32_e32 v154, v33
	v_mov_b32_e32 v155, v65
	s_waitcnt lgkmcnt(0)
; template <bool BWD, int MODE  >
; __device__ __forceinline__ void ssm_pass(const bf16* proj, int rowbase, int g, const bf16x8* BBp, const bf16x8* CCp, float ar, float ai, float& sr, float& si,
;                                          LAS unsigned* XS, int lane, f32x4* ysc, const float* Dp, bf16* zbuf) {
;     ...
;     for (int c = 0; c < 16; ++c) {
;         const int ch = BWD ? 15 - c : c;
;         bf16x8 unext = ucur;
;         if (c < 15) unext = *(const bf16x8*)(up + (size_t)(BWD ? ch - 1 : ch + 1) * 32 * DIN);
;         f32x4 y0 = (f32x4){0.f, 0.f, 0.f, 0.f}, y1 = y0; bf16 uvl[8];
;         if (MODE == 2) {
;             y0 = ysc[(ch * 2 + 0) * 64 + lane]; y1 = ysc[(ch * 2 + 1) * 64 + lane];
; #pragma unroll
;             for (int q = 0; q < 8; ++q) uvl[q] = proj[(size_t)(rowbase + 32 * ch + 16 * (q >> 2) + 4 * (lane >> 4) + (q & 3)) * DIN + 768 + g * 16 + (lane & 15)];
;         }
;         f32x16 z16;
; #pragma unroll
;         for (int r = 0; r < 16; ++r) z16[r] = 0.f;
;         const f32x16 x0 = __builtin_amdgcn_mfma_f32_32x32x16_bf16(ucur, bb[0], z16, 0, 0, 0);
;         const f32x16 x1 = __builtin_amdgcn_mfma_f32_32x32x16_bf16(ucur, bb[1], z16, 0, 0, 0);
;         const f32x16 x2 = __builtin_amdgcn_mfma_f32_32x32x16_bf16(ucur, bb[2], z16, 0, 0, 0);
;         const f32x16 x3 = __builtin_amdgcn_mfma_f32_32x32x16_bf16(ucur, bb[3], z16, 0, 0, 0);
; #pragma unroll
;         for (int r = 0; r < 16; ++r) { const int t = crow(r, hi); XS[t * XS_STRIDE + ql] = pk2(x0[r], x2[r]); XS[t * XS_STRIDE + 32 + ql] = pk2(x1[r], x3[r]); }
;         LDS_FENCE();
; #pragma unroll
;         for (int tt = 0; tt < 32; ++tt) {
;             const int t = BWD ? 31 - tt : tt;
;     ...
;         if (MODE > 0) {
;             LDS_FENCE();
;             const LAS unsigned char* ab = (const LAS unsigned char*)XS + (lane & 15) * (XS_STRIDE * 4) + (lane >> 4) * 16;
; #pragma unroll
;             for (int kk = 0; kk < 4; ++kk) {
;                 const bf16x8 a0 = *(const LAS bf16x8*)(ab + kk * 64), a1 = *(const LAS bf16x8*)(ab + 16 * XS_STRIDE * 4 + kk * 64);
;                 y0 = __builtin_amdgcn_mfma_f32_16x16x32_bf16(a0, cc[kk], y0, 0, 0, 0);
;                 y1 = __builtin_amdgcn_mfma_f32_16x16x32_bf16(a1, cc[kk], y1, 0, 0, 0);
;             }
;             if (MODE == 1) { ysc[(ch * 2 + 0) * 64 + lane] = y0; ysc[(ch * 2 + 1) * 64 + lane] = y1; }
	ds_read_b128 v[226:229], v178 offset:0
	ds_read_b128 v[242:245], v178 offset:4352
	ds_read_b128 v[230:233], v178 offset:64
	ds_read_b128 v[246:249], v178 offset:4416
	ds_read_b128 v[234:237], v178 offset:128
	ds_read_b128 v[250:253], v178 offset:4480
	ds_read_b128 v[238:241], v178 offset:192
	ds_read_b128 v[210:213], v178 offset:4544
	s_waitcnt lgkmcnt(6)
	v_mfma_f32_16x16x32_bf16 v[180:183], v[226:229], v[98:101], 0
	v_mfma_f32_16x16x32_bf16 v[184:187], v[242:245], v[114:117], 0
	s_waitcnt lgkmcnt(4)
	v_mfma_f32_16x16x32_bf16 v[180:183], v[230:233], v[102:105], v[180:183]
	v_mfma_f32_16x16x32_bf16 v[184:187], v[246:249], v[118:121], v[184:187]
	s_waitcnt lgkmcnt(2)
	v_mfma_f32_16x16x32_bf16 v[180:183], v[234:237], v[106:109], v[180:183]
	v_mfma_f32_16x16x32_bf16 v[184:187], v[250:253], v[122:125], v[184:187]
	s_waitcnt lgkmcnt(0)
	v_mfma_f32_16x16x32_bf16 v[180:183], v[238:241], v[110:113], v[180:183]
	v_mfma_f32_16x16x32_bf16 v[184:187], v[210:213], v[126:129], v[184:187]
	s_waitcnt vmcnt(0)
	v_mov_b32_e32 v130, v138
	v_mov_b32_e32 v131, v139
	v_mov_b32_e32 v132, v140
	v_mov_b32_e32 v133, v141
	v_mov_b32_e32 v134, v142
	v_mov_b32_e32 v135, v143
	v_mov_b32_e32 v136, v144
	v_mov_b32_e32 v137, v145
	s_nop 7
	global_store_dwordx4 v0, v[180:183], s[78:79]
	global_store_dwordx4 v0, v[184:187], s[78:79] offset:1024
	s_add_u32 s78, s78, 0x800
	s_addc_u32 s79, s79, 0
	s_add_i32 s32, s32, 1
	s_cmp_lt_u32 s32, 3
	s_cbranch_scc1 .Lp3n_loopa
.Lp3n_loopa3:
	v_add_u32_e32 v156, v157, v156
	s_mov_b64 exec, s[60:61]
	global_load_dwordx4 v[138:141], v156, s[6:7]
	s_mov_b64 exec, s[62:63]
	global_load_dwordx4 v[142:145], v156, s[6:7]
	s_mov_b64 exec, -1
	v_mfma_f32_32x32x16_bf16 v[2:17], v[130:133], v[66:69], 0
	v_mfma_f32_32x32x16_bf16 v[18:33], v[130:133], v[70:73], 0
	v_mfma_f32_32x32x16_bf16 v[34:49], v[130:133], v[74:77], 0
	v_mfma_f32_32x32x16_bf16 v[50:65], v[130:133], v[78:81], 0
	v_mfma_f32_32x32x16_bf16 v[2:17], v[134:137], v[82:85], v[2:17]
	v_mfma_f32_32x32x16_bf16 v[18:33], v[134:137], v[86:89], v[18:33]
	v_mfma_f32_32x32x16_bf16 v[34:49], v[134:137], v[90:93], v[34:49]
	v_mfma_f32_32x32x16_bf16 v[50:65], v[134:137], v[94:97], v[50:65]
	s_nop 15
	s_nop 7
	v_fmac_f32_e32 v2, v150, v153
	v_fmac_f32_e32 v18, v151, v155
	v_fmac_f32_e32 v34, v147, v152
	v_fmac_f32_e32 v50, v149, v154
	v_fmac_f32_e32 v2, v146, v152
	v_fmac_f32_e32 v18, v148, v154
	v_fmac_f32_e32 v34, v146, v153
	v_fmac_f32_e32 v50, v148, v155
	v_fmac_f32_e32 v3, v150, v34
	v_fmac_f32_e32 v19, v151, v50
	v_fmac_f32_e32 v35, v147, v2
	v_fmac_f32_e32 v51, v149, v18
	v_fmac_f32_e32 v3, v146, v2
	v_fmac_f32_e32 v19, v148, v18
	v_fmac_f32_e32 v35, v146, v34
	v_fmac_f32_e32 v51, v148, v50
	v_cvt_pk_bf16_f32 v214, v2, v34
	v_cvt_pk_bf16_f32 v215, v18, v50
	ds_write2_b32 v158, v214, v215 offset0:0 offset1:32
	v_fmac_f32_e32 v4, v150, v35
	v_fmac_f32_e32 v20, v151, v51
	v_fmac_f32_e32 v36, v147, v3
	v_fmac_f32_e32 v52, v149, v19
	v_fmac_f32_e32 v4, v146, v3
	v_fmac_f32_e32 v20, v148, v19
	v_fmac_f32_e32 v36, v146, v35
	v_fmac_f32_e32 v52, v148, v51
	v_cvt_pk_bf16_f32 v216, v3, v35
	v_cvt_pk_bf16_f32 v217, v19, v51
	ds_write2_b32 v158, v216, v217 offset0:68 offset1:100
	v_fmac_f32_e32 v5, v150, v36
	v_fmac_f32_e32 v21, v151, v52
	v_fmac_f32_e32 v37, v147, v4
	v_fmac_f32_e32 v53, v149, v20
	v_fmac_f32_e32 v5, v146, v4
	v_fmac_f32_e32 v21, v148, v20
	v_fmac_f32_e32 v37, v146, v36
	v_fmac_f32_e32 v53, v148, v52
	v_cvt_pk_bf16_f32 v214, v4, v36
	v_cvt_pk_bf16_f32 v215, v20, v52
	ds_write2_b32 v158, v214, v215 offset0:136 offset1:168
	v_fmac_f32_e32 v6, v150, v37
	v_fmac_f32_e32 v22, v151, v53
	v_fmac_f32_e32 v38, v147, v5
	v_fmac_f32_e32 v54, v149, v21
	v_fmac_f32_e32 v6, v146, v5
	v_fmac_f32_e32 v22, v148, v21
	v_fmac_f32_e32 v38, v146, v37
	v_fmac_f32_e32 v54, v148, v53
	v_cvt_pk_bf16_f32 v216, v5, v37
	v_cvt_pk_bf16_f32 v217, v21, v53
	ds_write2_b32 v158, v216, v217 offset0:204 offset1:236
	v_fmac_f32_e32 v7, v150, v38
	v_fmac_f32_e32 v23, v151, v54
	v_fmac_f32_e32 v39, v147, v6
	v_fmac_f32_e32 v55, v149, v22
	v_fmac_f32_e32 v7, v146, v6
	v_fmac_f32_e32 v23, v148, v22
	v_fmac_f32_e32 v39, v146, v38
	v_fmac_f32_e32 v55, v148, v54
	v_cvt_pk_bf16_f32 v214, v6, v38
	v_cvt_pk_bf16_f32 v215, v22, v54
	ds_write2_b32 v159, v214, v215 offset0:0 offset1:32
	v_fmac_f32_e32 v8, v150, v39
	v_fmac_f32_e32 v24, v151, v55
	v_fmac_f32_e32 v40, v147, v7
	v_fmac_f32_e32 v56, v149, v23
	v_fmac_f32_e32 v8, v146, v7
	v_fmac_f32_e32 v24, v148, v23
	v_fmac_f32_e32 v40, v146, v39
	v_fmac_f32_e32 v56, v148, v55
	v_cvt_pk_bf16_f32 v216, v7, v39
	v_cvt_pk_bf16_f32 v217, v23, v55
	ds_write2_b32 v159, v216, v217 offset0:68 offset1:100
	v_fmac_f32_e32 v9, v150, v40
	v_fmac_f32_e32 v25, v151, v56
	v_fmac_f32_e32 v41, v147, v8
	v_fmac_f32_e32 v57, v149, v24
	v_fmac_f32_e32 v9, v146, v8
	v_fmac_f32_e32 v25, v148, v24
; #define LAS __attribute__((address_space(3)))
; __device__ __forceinline__ unsigned pk2(float lo, float hi) { const f32x2 v = {lo, hi}; return __builtin_bit_cast(unsigned, __builtin_convertvector(v, bf16x2_t)); }
; __device__ __forceinline__ float bflo(unsigned w) { return __uint_as_float(w << 16); }
; __device__ __forceinline__ float bfhi(unsigned w) { return __uint_as_float(w & 0xffff0000u); }
; #define LDS_FENCE() asm volatile("s_waitcnt lgkmcnt(0)" ::: "memory")
; __device__ __forceinline__ int crow(int r, int hi) { return (r & 3) + 8 * (r >> 2) + 4 * hi; }
; template <bool BWD, int MODE  >
; __device__ __forceinline__ void ssm_pass(const bf16* proj, int rowbase, int g, const bf16x8* BBp, const bf16x8* CCp, float ar, float ai, float& sr, float& si,
;                                          LAS unsigned* XS, int lane, f32x4* ysc, const float* Dp, bf16* zbuf) {
;     ...
;         for (int r = 0; r < 16; ++r) { const int t = crow(r, hi); XS[t * XS_STRIDE + ql] = pk2(x0[r], x2[r]); XS[t * XS_STRIDE + 32 + ql] = pk2(x1[r], x3[r]); }
;         LDS_FENCE();
; #pragma unroll
;         for (int tt = 0; tt < 32; ++tt) {
;             const int t = BWD ? 31 - tt : tt;
;             const unsigned v = XS[t * XS_STRIDE + lane];
;             const float nr = fmaf(ar, sr, fmaf(-ai, si, bflo(v))), ni = fmaf(ar, si, fmaf(ai, sr, bfhi(v)));
;             sr = nr; si = ni;
;             if (MODE > 0) XS[t * XS_STRIDE + lane] = pk2(sr, si);
;         }
;         if (MODE > 0) {
;             LDS_FENCE();
;             const LAS unsigned char* ab = (const LAS unsigned char*)XS + (lane & 15) * (XS_STRIDE * 4) + (lane >> 4) * 16;
; #pragma unroll
;             for (int kk = 0; kk < 4; ++kk) {
;                 const bf16x8 a0 = *(const LAS bf16x8*)(ab + kk * 64), a1 = *(const LAS bf16x8*)(ab + 16 * XS_STRIDE * 4 + kk * 64);
;                 y0 = __builtin_amdgcn_mfma_f32_16x16x32_bf16(a0, cc[kk], y0, 0, 0, 0);
;                 y1 = __builtin_amdgcn_mfma_f32_16x16x32_bf16(a1, cc[kk], y1, 0, 0, 0);
;             }
;             if (MODE == 1) { ysc[(ch * 2 + 0) * 64 + lane] = y0; ysc[(ch * 2 + 1) * 64 + lane] = y1; }
	v_fmac_f32_e32 v41, v146, v40
	v_fmac_f32_e32 v57, v148, v56
	v_cvt_pk_bf16_f32 v214, v8, v40
	v_cvt_pk_bf16_f32 v215, v24, v56
	ds_write2_b32 v159, v214, v215 offset0:136 offset1:168
	v_fmac_f32_e32 v10, v150, v41
	v_fmac_f32_e32 v26, v151, v57
	v_fmac_f32_e32 v42, v147, v9
	v_fmac_f32_e32 v58, v149, v25
	v_fmac_f32_e32 v10, v146, v9
	v_fmac_f32_e32 v26, v148, v25
	v_fmac_f32_e32 v42, v146, v41
	v_fmac_f32_e32 v58, v148, v57
	v_cvt_pk_bf16_f32 v216, v9, v41
	v_cvt_pk_bf16_f32 v217, v25, v57
	ds_write2_b32 v159, v216, v217 offset0:204 offset1:236
	v_fmac_f32_e32 v11, v150, v42
	v_fmac_f32_e32 v27, v151, v58
	v_fmac_f32_e32 v43, v147, v10
	v_fmac_f32_e32 v59, v149, v26
	v_fmac_f32_e32 v11, v146, v10
	v_fmac_f32_e32 v27, v148, v26
	v_fmac_f32_e32 v43, v146, v42
	v_fmac_f32_e32 v59, v148, v58
	v_cvt_pk_bf16_f32 v214, v10, v42
	v_cvt_pk_bf16_f32 v215, v26, v58
	ds_write2_b32 v160, v214, v215 offset0:0 offset1:32
	v_fmac_f32_e32 v12, v150, v43
	v_fmac_f32_e32 v28, v151, v59
	v_fmac_f32_e32 v44, v147, v11
	v_fmac_f32_e32 v60, v149, v27
	v_fmac_f32_e32 v12, v146, v11
	v_fmac_f32_e32 v28, v148, v27
	v_fmac_f32_e32 v44, v146, v43
	v_fmac_f32_e32 v60, v148, v59
	v_cvt_pk_bf16_f32 v216, v11, v43
	v_cvt_pk_bf16_f32 v217, v27, v59
	ds_write2_b32 v160, v216, v217 offset0:68 offset1:100
	v_fmac_f32_e32 v13, v150, v44
	v_fmac_f32_e32 v29, v151, v60
	v_fmac_f32_e32 v45, v147, v12
	v_fmac_f32_e32 v61, v149, v28
	v_fmac_f32_e32 v13, v146, v12
	v_fmac_f32_e32 v29, v148, v28
	v_fmac_f32_e32 v45, v146, v44
	v_fmac_f32_e32 v61, v148, v60
	v_cvt_pk_bf16_f32 v214, v12, v44
	v_cvt_pk_bf16_f32 v215, v28, v60
	ds_write2_b32 v160, v214, v215 offset0:136 offset1:168
	v_fmac_f32_e32 v14, v150, v45
	v_fmac_f32_e32 v30, v151, v61
	v_fmac_f32_e32 v46, v147, v13
	v_fmac_f32_e32 v62, v149, v29
	v_fmac_f32_e32 v14, v146, v13
	v_fmac_f32_e32 v30, v148, v29
	v_fmac_f32_e32 v46, v146, v45
	v_fmac_f32_e32 v62, v148, v61
	v_cvt_pk_bf16_f32 v216, v13, v45
	v_cvt_pk_bf16_f32 v217, v29, v61
	ds_write2_b32 v160, v216, v217 offset0:204 offset1:236
	v_fmac_f32_e32 v15, v150, v46
	v_fmac_f32_e32 v31, v151, v62
	v_fmac_f32_e32 v47, v147, v14
	v_fmac_f32_e32 v63, v149, v30
	v_fmac_f32_e32 v15, v146, v14
	v_fmac_f32_e32 v31, v148, v30
	v_fmac_f32_e32 v47, v146, v46
	v_fmac_f32_e32 v63, v148, v62
	v_cvt_pk_bf16_f32 v214, v14, v46
	v_cvt_pk_bf16_f32 v215, v30, v62
	ds_write2_b32 v161, v214, v215 offset0:0 offset1:32
	v_fmac_f32_e32 v16, v150, v47
	v_fmac_f32_e32 v32, v151, v63
	v_fmac_f32_e32 v48, v147, v15
	v_fmac_f32_e32 v64, v149, v31
	v_fmac_f32_e32 v16, v146, v15
	v_fmac_f32_e32 v32, v148, v31
	v_fmac_f32_e32 v48, v146, v47
	v_fmac_f32_e32 v64, v148, v63
	v_cvt_pk_bf16_f32 v216, v15, v47
	v_cvt_pk_bf16_f32 v217, v31, v63
	ds_write2_b32 v161, v216, v217 offset0:68 offset1:100
	v_fmac_f32_e32 v17, v150, v48
	v_fmac_f32_e32 v33, v151, v64
	v_fmac_f32_e32 v49, v147, v16
	v_fmac_f32_e32 v65, v149, v32
	v_fmac_f32_e32 v17, v146, v16
	v_fmac_f32_e32 v33, v148, v32
	v_fmac_f32_e32 v49, v146, v48
	v_fmac_f32_e32 v65, v148, v64
	v_cvt_pk_bf16_f32 v214, v16, v48
	v_cvt_pk_bf16_f32 v215, v32, v64
	ds_write2_b32 v161, v214, v215 offset0:136 offset1:168
	v_cvt_pk_bf16_f32 v216, v17, v49
	v_cvt_pk_bf16_f32 v217, v33, v65
	ds_write2_b32 v161, v216, v217 offset0:204 offset1:236
	v_mov_b32_e32 v152, v17
	v_mov_b32_e32 v153, v49
	v_mov_b32_e32 v154, v33
	v_mov_b32_e32 v155, v65
	s_waitcnt lgkmcnt(0)
	ds_read_b128 v[226:229], v178 offset:0
	ds_read_b128 v[242:245], v178 offset:4352
	ds_read_b128 v[230:233], v178 offset:64
	ds_read_b128 v[246:249], v178 offset:4416
	ds_read_b128 v[234:237], v178 offset:128
	ds_read_b128 v[250:253], v178 offset:4480
	ds_read_b128 v[238:241], v178 offset:192
	ds_read_b128 v[210:213], v178 offset:4544
	s_waitcnt lgkmcnt(6)
	v_mfma_f32_16x16x32_bf16 v[180:183], v[226:229], v[98:101], 0
	v_mfma_f32_16x16x32_bf16 v[184:187], v[242:245], v[114:117], 0
	s_waitcnt lgkmcnt(4)
	v_mfma_f32_16x16x32_bf16 v[180:183], v[230:233], v[102:105], v[180:183]
	v_mfma_f32_16x16x32_bf16 v[184:187], v[246:249], v[118:121], v[184:187]
	s_waitcnt lgkmcnt(2)
	v_mfma_f32_16x16x32_bf16 v[180:183], v[234:237], v[106:109], v[180:183]
	v_mfma_f32_16x16x32_bf16 v[184:187], v[250:253], v[122:125], v[184:187]
	s_waitcnt lgkmcnt(0)
	v_mfma_f32_16x16x32_bf16 v[180:183], v[238:241], v[110:113], v[180:183]
	v_mfma_f32_16x16x32_bf16 v[184:187], v[210:213], v[126:129], v[184:187]
	s_waitcnt vmcnt(0)
	v_mov_b32_e32 v130, v138
	v_mov_b32_e32 v131, v139
	v_mov_b32_e32 v132, v140
	v_mov_b32_e32 v133, v141
	v_mov_b32_e32 v134, v142
	v_mov_b32_e32 v135, v143
	v_mov_b32_e32 v136, v144
	v_mov_b32_e32 v137, v145
	s_nop 7
	s_lshl_b32 s26, s18, 11
	s_add_i32 s26, s26, 0x15000
	v_add_u32_e32 v179, s26, v0
	ds_write_b128 v179, v[180:183]
	ds_write_b128 v179, v[184:187] offset:1024
	s_add_i32 s32, s32, 1

; __device__ __forceinline__ unsigned pk2(float lo, float hi) { const f32x2 v = {lo, hi}; return __builtin_bit_cast(unsigned, __builtin_convertvector(v, bf16x2_t)); }
; __device__ __forceinline__ float bflo(unsigned w) { return __uint_as_float(w << 16); }
; __device__ __forceinline__ float bfhi(unsigned w) { return __uint_as_float(w & 0xffff0000u); }
; #define LDS_FENCE() asm volatile("s_waitcnt lgkmcnt(0)" ::: "memory")
; template <bool BWD, int MODE  >
; __device__ __forceinline__ void ssm_pass(const bf16* proj, int rowbase, int g, const bf16x8* BBp, const bf16x8* CCp, float ar, float ai, float& sr, float& si,
;                                          LAS unsigned* XS, int lane, f32x4* ysc, const float* Dp, bf16* zbuf) {
;     ...
;     for (int c = 0; c < 16; ++c) {
;         const int ch = BWD ? 15 - c : c;
;         bf16x8 unext = ucur;
;         if (c < 15) unext = *(const bf16x8*)(up + (size_t)(BWD ? ch - 1 : ch + 1) * 32 * DIN);
;         f32x4 y0 = (f32x4){0.f, 0.f, 0.f, 0.f}, y1 = y0; bf16 uvl[8];
;         if (MODE == 2) {
;             y0 = ysc[(ch * 2 + 0) * 64 + lane]; y1 = ysc[(ch * 2 + 1) * 64 + lane];
; #pragma unroll
;             for (int q = 0; q < 8; ++q) uvl[q] = proj[(size_t)(rowbase + 32 * ch + 16 * (q >> 2) + 4 * (lane >> 4) + (q & 3)) * DIN + 768 + g * 16 + (lane & 15)];
;         }
;         f32x16 z16;
; #pragma unroll
;         for (int r = 0; r < 16; ++r) z16[r] = 0.f;
;         const f32x16 x0 = __builtin_amdgcn_mfma_f32_32x32x16_bf16(ucur, bb[0], z16, 0, 0, 0);
;         const f32x16 x1 = __builtin_amdgcn_mfma_f32_32x32x16_bf16(ucur, bb[1], z16, 0, 0, 0);
;         const f32x16 x2 = __builtin_amdgcn_mfma_f32_32x32x16_bf16(ucur, bb[2], z16, 0, 0, 0);
;         const f32x16 x3 = __builtin_amdgcn_mfma_f32_32x32x16_bf16(ucur, bb[3], z16, 0, 0, 0);
; #pragma unroll
;         for (int r = 0; r < 16; ++r) { const int t = crow(r, hi); XS[t * XS_STRIDE + ql] = pk2(x0[r], x2[r]); XS[t * XS_STRIDE + 32 + ql] = pk2(x1[r], x3[r]); }
;         LDS_FENCE();
; #pragma unroll
;         for (int tt = 0; tt < 32; ++tt) {
;             const int t = BWD ? 31 - tt : tt;
;             const unsigned v = XS[t * XS_STRIDE + lane];
;             const float nr = fmaf(ar, sr, fmaf(-ai, si, bflo(v))), ni = fmaf(ar, si, fmaf(ai, sr, bfhi(v)));
;             sr = nr; si = ni;
;             if (MODE > 0) XS[t * XS_STRIDE + lane] = pk2(sr, si);
.Lp3n_nopfb4:
	s_lshl_b32 s26, s18, 11
	s_add_i32 s26, s26, 0x15000
	v_add_u32_e32 v179, s26, v225
	ds_read_b128 v[188:191], v179 offset:1024
	ds_read_b128 v[192:195], v179
	global_load_ushort v196, v206, s[6:7]
	global_load_ushort v197, v206, s[6:7] offset:2560
	global_load_ushort v198, v206, s[80:81]
	global_load_ushort v199, v206, s[80:81] offset:2560
	global_load_ushort v200, v207, s[6:7]
	global_load_ushort v201, v207, s[6:7] offset:-2560
	global_load_ushort v202, v207, s[82:83]
	global_load_ushort v203, v207, s[82:83] offset:-2560
	v_mfma_f32_32x32x16_bf16 v[2:17], v[130:133], v[66:69], 0
	v_mfma_f32_32x32x16_bf16 v[18:33], v[130:133], v[70:73], 0
	v_mfma_f32_32x32x16_bf16 v[34:49], v[130:133], v[74:77], 0
	v_mfma_f32_32x32x16_bf16 v[50:65], v[130:133], v[78:81], 0
	v_mfma_f32_32x32x16_bf16 v[2:17], v[134:137], v[82:85], v[2:17]
	v_mfma_f32_32x32x16_bf16 v[18:33], v[134:137], v[86:89], v[18:33]
	v_mfma_f32_32x32x16_bf16 v[34:49], v[134:137], v[90:93], v[34:49]
	v_mfma_f32_32x32x16_bf16 v[50:65], v[134:137], v[94:97], v[50:65]
	s_nop 15
	s_nop 7
	v_fmac_f32_e32 v2, v150, v153
	v_fmac_f32_e32 v18, v151, v155
	v_fmac_f32_e32 v34, v147, v152
	v_fmac_f32_e32 v50, v149, v154
	v_fmac_f32_e32 v2, v146, v152
	v_fmac_f32_e32 v18, v148, v154
	v_fmac_f32_e32 v34, v146, v153
	v_fmac_f32_e32 v50, v148, v155
	v_fmac_f32_e32 v3, v150, v34
	v_fmac_f32_e32 v19, v151, v50
	v_fmac_f32_e32 v35, v147, v2
	v_fmac_f32_e32 v51, v149, v18
	v_fmac_f32_e32 v3, v146, v2
	v_fmac_f32_e32 v19, v148, v18
	v_fmac_f32_e32 v35, v146, v34
	v_fmac_f32_e32 v51, v148, v50
	v_cvt_pk_bf16_f32 v214, v2, v34
	v_cvt_pk_bf16_f32 v215, v18, v50
	ds_write2_b32 v158, v214, v215 offset0:0 offset1:32
	v_fmac_f32_e32 v4, v150, v35
	v_fmac_f32_e32 v20, v151, v51
	v_fmac_f32_e32 v36, v147, v3
	v_fmac_f32_e32 v52, v149, v19
	v_fmac_f32_e32 v4, v146, v3
	v_fmac_f32_e32 v20, v148, v19
	v_fmac_f32_e32 v36, v146, v35
	v_fmac_f32_e32 v52, v148, v51
	v_cvt_pk_bf16_f32 v216, v3, v35
	v_cvt_pk_bf16_f32 v217, v19, v51
	ds_write2_b32 v158, v216, v217 offset0:68 offset1:100
	v_fmac_f32_e32 v5, v150, v36
	v_fmac_f32_e32 v21, v151, v52
	v_fmac_f32_e32 v37, v147, v4
	v_fmac_f32_e32 v53, v149, v20
	v_fmac_f32_e32 v5, v146, v4
	v_fmac_f32_e32 v21, v148, v20
	v_fmac_f32_e32 v37, v146, v36
	v_fmac_f32_e32 v53, v148, v52
	v_cvt_pk_bf16_f32 v214, v4, v36
	v_cvt_pk_bf16_f32 v215, v20, v52
	ds_write2_b32 v158, v214, v215 offset0:136 offset1:168
	v_fmac_f32_e32 v6, v150, v37
	v_fmac_f32_e32 v22, v151, v53
	v_fmac_f32_e32 v38, v147, v5
	v_fmac_f32_e32 v54, v149, v21
	v_fmac_f32_e32 v6, v146, v5
	v_fmac_f32_e32 v22, v148, v21
	v_fmac_f32_e32 v38, v146, v37
	v_fmac_f32_e32 v54, v148, v53
	v_cvt_pk_bf16_f32 v216, v5, v37
	v_cvt_pk_bf16_f32 v217, v21, v53
	ds_write2_b32 v158, v216, v217 offset0:204 offset1:236
	v_fmac_f32_e32 v7, v150, v38
	v_fmac_f32_e32 v23, v151, v54
	v_fmac_f32_e32 v39, v147, v6
	v_fmac_f32_e32 v55, v149, v22
	v_fmac_f32_e32 v7, v146, v6
	v_fmac_f32_e32 v23, v148, v22
	v_fmac_f32_e32 v39, v146, v38
	v_fmac_f32_e32 v55, v148, v54
	v_cvt_pk_bf16_f32 v214, v6, v38
	v_cvt_pk_bf16_f32 v215, v22, v54
	ds_write2_b32 v159, v214, v215 offset0:0 offset1:32
	v_fmac_f32_e32 v8, v150, v39
	v_fmac_f32_e32 v24, v151, v55
	v_fmac_f32_e32 v40, v147, v7
	v_fmac_f32_e32 v56, v149, v23
	v_fmac_f32_e32 v8, v146, v7
	v_fmac_f32_e32 v24, v148, v23
	v_fmac_f32_e32 v40, v146, v39
	v_fmac_f32_e32 v56, v148, v55
	v_cvt_pk_bf16_f32 v216, v7, v39
	v_cvt_pk_bf16_f32 v217, v23, v55
	ds_write2_b32 v159, v216, v217 offset0:68 offset1:100
	v_fmac_f32_e32 v9, v150, v40
	v_fmac_f32_e32 v25, v151, v56
	v_fmac_f32_e32 v41, v147, v8
	v_fmac_f32_e32 v57, v149, v24
	v_fmac_f32_e32 v9, v146, v8
	v_fmac_f32_e32 v25, v148, v24
	v_fmac_f32_e32 v41, v146, v40
	v_fmac_f32_e32 v57, v148, v56
	v_cvt_pk_bf16_f32 v214, v8, v40
	v_cvt_pk_bf16_f32 v215, v24, v56
	ds_write2_b32 v159, v214, v215 offset0:136 offset1:168
	v_fmac_f32_e32 v10, v150, v41
	v_fmac_f32_e32 v26, v151, v57
	v_fmac_f32_e32 v42, v147, v9
	v_fmac_f32_e32 v58, v149, v25
	v_fmac_f32_e32 v10, v146, v9
	v_fmac_f32_e32 v26, v148, v25
	v_fmac_f32_e32 v42, v146, v41
	v_fmac_f32_e32 v58, v148, v57
	v_cvt_pk_bf16_f32 v216, v9, v41
	v_cvt_pk_bf16_f32 v217, v25, v57
	ds_write2_b32 v159, v216, v217 offset0:204 offset1:236
	v_fmac_f32_e32 v11, v150, v42
	v_fmac_f32_e32 v27, v151, v58
	v_fmac_f32_e32 v43, v147, v10
	v_fmac_f32_e32 v59, v149, v26
	v_fmac_f32_e32 v11, v146, v10
	v_fmac_f32_e32 v27, v148, v26
	v_fmac_f32_e32 v43, v146, v42
	v_fmac_f32_e32 v59, v148, v58
	v_cvt_pk_bf16_f32 v214, v10, v42
	v_cvt_pk_bf16_f32 v215, v26, v58
	ds_write2_b32 v160, v214, v215 offset0:0 offset1:32
	v_fmac_f32_e32 v12, v150, v43
	v_fmac_f32_e32 v28, v151, v59
	v_fmac_f32_e32 v44, v147, v11
	v_fmac_f32_e32 v60, v149, v27
	v_fmac_f32_e32 v12, v146, v11
	v_fmac_f32_e32 v28, v148, v27
	v_fmac_f32_e32 v44, v146, v43
	v_fmac_f32_e32 v60, v148, v59
	v_cvt_pk_bf16_f32 v216, v11, v43
	v_cvt_pk_bf16_f32 v217, v27, v59
	ds_write2_b32 v160, v216, v217 offset0:68 offset1:100
	v_fmac_f32_e32 v13, v150, v44
	v_fmac_f32_e32 v29, v151, v60
	v_fmac_f32_e32 v45, v147, v12
	v_fmac_f32_e32 v61, v149, v28
	v_fmac_f32_e32 v13, v146, v12
	v_fmac_f32_e32 v29, v148, v28
	v_fmac_f32_e32 v45, v146, v44
	v_fmac_f32_e32 v61, v148, v60
	v_cvt_pk_bf16_f32 v214, v12, v44
	v_cvt_pk_bf16_f32 v215, v28, v60
	ds_write2_b32 v160, v214, v215 offset0:136 offset1:168
	v_fmac_f32_e32 v14, v150, v45
	v_fmac_f32_e32 v30, v151, v61
	v_fmac_f32_e32 v46, v147, v13
	v_fmac_f32_e32 v62, v149, v29
	v_fmac_f32_e32 v14, v146, v13
	v_fmac_f32_e32 v30, v148, v29
	v_fmac_f32_e32 v46, v146, v45
	v_fmac_f32_e32 v62, v148, v61
	v_cvt_pk_bf16_f32 v216, v13, v45
; #define LAS __attribute__((address_space(3)))
; __device__ __forceinline__ unsigned f2bf(float f) { unsigned u = __builtin_bit_cast(unsigned, f); return (u + 0x7fffu + ((u >> 16) & 1u)) >> 16; }
; __device__ __forceinline__ float bf2f(bf16 v) { return __uint_as_float((unsigned)v << 16); }
; #define LDS_FENCE() asm volatile("s_waitcnt lgkmcnt(0)" ::: "memory")
; template <bool BWD, int MODE  >
; __device__ __forceinline__ void ssm_pass(const bf16* proj, int rowbase, int g, const bf16x8* BBp, const bf16x8* CCp, float ar, float ai, float& sr, float& si,
;                                          LAS unsigned* XS, int lane, f32x4* ysc, const float* Dp, bf16* zbuf) {
;     ...
;         if (MODE > 0) {
;             LDS_FENCE();
;             const LAS unsigned char* ab = (const LAS unsigned char*)XS + (lane & 15) * (XS_STRIDE * 4) + (lane >> 4) * 16;
; #pragma unroll
;             for (int kk = 0; kk < 4; ++kk) {
;                 const bf16x8 a0 = *(const LAS bf16x8*)(ab + kk * 64), a1 = *(const LAS bf16x8*)(ab + 16 * XS_STRIDE * 4 + kk * 64);
;                 y0 = __builtin_amdgcn_mfma_f32_16x16x32_bf16(a0, cc[kk], y0, 0, 0, 0);
;                 y1 = __builtin_amdgcn_mfma_f32_16x16x32_bf16(a1, cc[kk], y1, 0, 0, 0);
;             }
;             if (MODE == 1) { ysc[(ch * 2 + 0) * 64 + lane] = y0; ysc[(ch * 2 + 1) * 64 + lane] = y1; }
;             else {
;                 const int hcol = g * 16 + (lane & 15);
; #pragma unroll
;                 for (int rt = 0; rt < 2; ++rt)
; #pragma unroll
;                     for (int i = 0; i < 4; ++i) {
;                         const int row = rowbase + 32 * ch + 16 * rt + 4 * (lane >> 4) + i;
;                         const float uv = bf2f(uvl[rt * 4 + i]);
;                         const float y = (rt ? y1[i] : y0[i]) + dval * uv;
;                         const float zz = y * __builtin_amdgcn_rcpf(1.0f + __builtin_amdgcn_exp2f(-2.3022082f * (y + 0.044715f * y * y * y)));
;                         zbuf[(size_t)row * 512 + hcol] = (bf16)f2bf(zz);
;                     }
	v_cvt_pk_bf16_f32 v217, v29, v61
	ds_write2_b32 v160, v216, v217 offset0:204 offset1:236
	v_fmac_f32_e32 v15, v150, v46
	v_fmac_f32_e32 v31, v151, v62
	v_fmac_f32_e32 v47, v147, v14
	v_fmac_f32_e32 v63, v149, v30
	v_fmac_f32_e32 v15, v146, v14
	v_fmac_f32_e32 v31, v148, v30
	v_fmac_f32_e32 v47, v146, v46
	v_fmac_f32_e32 v63, v148, v62
	v_cvt_pk_bf16_f32 v214, v14, v46
	v_cvt_pk_bf16_f32 v215, v30, v62
	ds_write2_b32 v161, v214, v215 offset0:0 offset1:32
	v_fmac_f32_e32 v16, v150, v47
	v_fmac_f32_e32 v32, v151, v63
	v_fmac_f32_e32 v48, v147, v15
	v_fmac_f32_e32 v64, v149, v31
	v_fmac_f32_e32 v16, v146, v15
	v_fmac_f32_e32 v32, v148, v31
	v_fmac_f32_e32 v48, v146, v47
	v_fmac_f32_e32 v64, v148, v63
	v_cvt_pk_bf16_f32 v216, v15, v47
	v_cvt_pk_bf16_f32 v217, v31, v63
	ds_write2_b32 v161, v216, v217 offset0:68 offset1:100
	v_fmac_f32_e32 v17, v150, v48
	v_fmac_f32_e32 v33, v151, v64
	v_fmac_f32_e32 v49, v147, v16
	v_fmac_f32_e32 v65, v149, v32
	v_fmac_f32_e32 v17, v146, v16
	v_fmac_f32_e32 v33, v148, v32
	v_fmac_f32_e32 v49, v146, v48
	v_fmac_f32_e32 v65, v148, v64
	v_cvt_pk_bf16_f32 v214, v16, v48
	v_cvt_pk_bf16_f32 v215, v32, v64
	ds_write2_b32 v161, v214, v215 offset0:136 offset1:168
	v_cvt_pk_bf16_f32 v216, v17, v49
	v_cvt_pk_bf16_f32 v217, v33, v65
	ds_write2_b32 v161, v216, v217 offset0:204 offset1:236
	v_mov_b32_e32 v152, v17
	v_mov_b32_e32 v153, v49
	v_mov_b32_e32 v154, v33
	v_mov_b32_e32 v155, v65
	s_waitcnt lgkmcnt(0)
	ds_read_b128 v[226:229], v178 offset:0
	ds_read_b128 v[242:245], v178 offset:4352
	ds_read_b128 v[230:233], v178 offset:64
	ds_read_b128 v[246:249], v178 offset:4416
	ds_read_b128 v[234:237], v178 offset:128
	ds_read_b128 v[250:253], v178 offset:4480
	ds_read_b128 v[238:241], v178 offset:192
	ds_read_b128 v[210:213], v178 offset:4544
	s_waitcnt lgkmcnt(6)
	v_mfma_f32_16x16x32_bf16 v[180:183], v[226:229], v[98:101], 0
	v_mfma_f32_16x16x32_bf16 v[184:187], v[242:245], v[114:117], 0
	s_waitcnt lgkmcnt(4)
	v_mfma_f32_16x16x32_bf16 v[180:183], v[230:233], v[102:105], v[180:183]
	v_mfma_f32_16x16x32_bf16 v[184:187], v[246:249], v[118:121], v[184:187]
	s_waitcnt lgkmcnt(2)
	v_mfma_f32_16x16x32_bf16 v[180:183], v[234:237], v[106:109], v[180:183]
	v_mfma_f32_16x16x32_bf16 v[184:187], v[250:253], v[122:125], v[184:187]
	s_waitcnt lgkmcnt(0)
	v_mfma_f32_16x16x32_bf16 v[180:183], v[238:241], v[110:113], v[180:183]
	v_mfma_f32_16x16x32_bf16 v[184:187], v[210:213], v[126:129], v[184:187]
	s_waitcnt vmcnt(0)
	v_mov_b32_e32 v130, v138
	v_mov_b32_e32 v131, v139
	v_mov_b32_e32 v132, v140
	v_mov_b32_e32 v133, v141
	v_mov_b32_e32 v134, v142
	v_mov_b32_e32 v135, v143
	v_mov_b32_e32 v136, v144
	v_mov_b32_e32 v137, v145
	s_nop 7
	v_add_f32_e32 v180, v180, v191
	v_add_f32_e32 v181, v181, v190
	v_add_f32_e32 v182, v182, v189
	v_add_f32_e32 v183, v183, v188
	v_add_f32_e32 v184, v184, v195
	v_add_f32_e32 v185, v185, v194
	v_add_f32_e32 v186, v186, v193
	v_add_f32_e32 v187, v187, v192
	v_lshlrev_b32_e32 v196, 16, v196
	v_lshlrev_b32_e32 v197, 16, v197
	v_lshlrev_b32_e32 v198, 16, v198
	v_lshlrev_b32_e32 v199, 16, v199
	v_lshlrev_b32_e32 v200, 16, v200
	v_lshlrev_b32_e32 v201, 16, v201
	v_lshlrev_b32_e32 v202, 16, v202
	v_lshlrev_b32_e32 v203, 16, v203
	v_fmac_f32_e32 v180, v208, v196
	v_fmac_f32_e32 v181, v208, v197
	v_fmac_f32_e32 v182, v208, v198
	v_fmac_f32_e32 v183, v208, v199
	v_fmac_f32_e32 v184, v208, v200
	v_fmac_f32_e32 v185, v208, v201
	v_fmac_f32_e32 v186, v208, v202
	v_fmac_f32_e32 v187, v208, v203
	v_mul_f32_e32 v226, 0x3d372713, v180
	v_mul_f32_e32 v227, 0x3d372713, v181
	v_mul_f32_e32 v228, 0x3d372713, v182
	v_mul_f32_e32 v229, 0x3d372713, v183
	v_mul_f32_e32 v230, 0x3d372713, v184
	v_mul_f32_e32 v231, 0x3d372713, v185
	v_mul_f32_e32 v232, 0x3d372713, v186
	v_mul_f32_e32 v233, 0x3d372713, v187
	v_mul_f32_e32 v226, v180, v226
	v_mul_f32_e32 v227, v181, v227
	v_mul_f32_e32 v228, v182, v228
	v_mul_f32_e32 v229, v183, v229
	v_mul_f32_e32 v230, v184, v230
	v_mul_f32_e32 v231, v185, v231
	v_mul_f32_e32 v232, v186, v232
	v_mul_f32_e32 v233, v187, v233
	v_fma_f32 v226, v180, v226, v180
	v_fma_f32 v227, v181, v227, v181
	v_fma_f32 v228, v182, v228, v182
	v_fma_f32 v229, v183, v229, v183
	v_fma_f32 v230, v184, v230, v184
	v_fma_f32 v231, v185, v231, v185
	v_fma_f32 v232, v186, v232, v186
	v_fma_f32 v233, v187, v233, v187
	v_mul_f32_e32 v226, 0xc0135761, v226
	v_mul_f32_e32 v227, 0xc0135761, v227
	v_mul_f32_e32 v228, 0xc0135761, v228
	v_mul_f32_e32 v229, 0xc0135761, v229
	v_mul_f32_e32 v230, 0xc0135761, v230
	v_mul_f32_e32 v231, 0xc0135761, v231
	v_mul_f32_e32 v232, 0xc0135761, v232
	v_mul_f32_e32 v233, 0xc0135761, v233
	v_exp_f32_e32 v226, v226
	v_exp_f32_e32 v227, v227
	v_exp_f32_e32 v228, v228
	v_exp_f32_e32 v229, v229
	v_exp_f32_e32 v230, v230
	v_exp_f32_e32 v231, v231
	v_exp_f32_e32 v232, v232
	v_exp_f32_e32 v233, v233
	v_add_f32_e32 v226, 1.0, v226
	v_add_f32_e32 v227, 1.0, v227
	v_add_f32_e32 v228, 1.0, v228
	v_add_f32_e32 v229, 1.0, v229
	v_add_f32_e32 v230, 1.0, v230
	v_add_f32_e32 v231, 1.0, v231
	v_add_f32_e32 v232, 1.0, v232
	v_add_f32_e32 v233, 1.0, v233
	v_rcp_f32_e32 v226, v226
	v_rcp_f32_e32 v227, v227
	v_rcp_f32_e32 v228, v228
	v_rcp_f32_e32 v229, v229
	v_rcp_f32_e32 v230, v230
	v_rcp_f32_e32 v231, v231
	v_rcp_f32_e32 v232, v232
	v_rcp_f32_e32 v233, v233
	v_mul_f32_e32 v226, v180, v226
	v_mul_f32_e32 v227, v181, v227
	v_mul_f32_e32 v228, v182, v228
	v_mul_f32_e32 v229, v183, v229
	v_mul_f32_e32 v230, v184, v230
	v_mul_f32_e32 v231, v185, v231
	v_mul_f32_e32 v232, v186, v232
	v_mul_f32_e32 v233, v187, v233
	v_cvt_pk_bf16_f32 v226, v226, v226
	v_cvt_pk_bf16_f32 v227, v227, v227
	v_cvt_pk_bf16_f32 v228, v228, v228
	v_cvt_pk_bf16_f32 v229, v229, v229
	v_cvt_pk_bf16_f32 v230, v230, v230
	v_cvt_pk_bf16_f32 v231, v231, v231
	v_cvt_pk_bf16_f32 v232, v232, v232
	v_cvt_pk_bf16_f32 v233, v233, v233
	global_store_short v204, v226, s[8:9]
	global_store_short v204, v227, s[8:9] offset:1024
	global_store_short v204, v228, s[8:9] offset:2048
	global_store_short v204, v229, s[8:9] offset:3072
	global_store_short v205, v230, s[8:9]
	global_store_short v205, v231, s[8:9] offset:-1024
	global_store_short v205, v232, s[8:9] offset:-2048
	global_store_short v205, v233, s[8:9] offset:-3072
	v_add_u32_e32 v204, 0x4000, v204
	v_add_u32_e32 v205, 0xffffc000, v205
	v_add_u32_e32 v206, 0xa000, v206
	v_add_u32_e32 v207, 0xffff6000, v207
	s_add_i32 s32, s32, 1
	s_sub_u32 s78, s78, 0x800
	s_subb_u32 s79, s79, 0
